# scan: next-chunk operand LDS-DMA issued by waves 4-7 only (14 pieces each) so waves 0-3 start their MFMAs at once
# baseline (speedup 1.0000x reference)
.LBB0_1090:
	v_mov_b32_e32 v40, v125
	s_add_i32 s64, s19, 1
	s_cmp_ge_u32 s64, s22
	v_and_b32_e32 v135, 15, v40
	v_ashrrev_i32_e32 v136, 4, v40
	s_cbranch_scc1 .LBB0_1092
	s_add_i32 s20, s63, s19
	s_ashr_i32 s21, s20, 31
	s_lshl_b64 s[58:59], s[20:21], 2
	s_add_u32 s58, s24, s58
	s_addc_u32 s59, s25, s59
	s_mul_hi_i32 s21, s20, 0x16000
	s_mul_i32 s20, s20, 0x16000
	v_lshlrev_b32_e32 v41, 4, v40
	s_add_u32 s20, s31, s20
	v_add_u32_e32 v42, s35, v41
	s_addc_u32 s21, s34, s21
	v_lshrrev_b32_e32 v43, 8, v42
	global_load_dword v134, v173, s[58:59]
	s_add_u32 s58, s20, 0x8000
	v_xor_b32_e32 v43, v43, v40
	s_addc_u32 s59, s21, 0
	v_lshlrev_b32_e32 v43, 4, v43
	v_and_b32_e32 v42, 0xffffff00, v42
	s_bitcmp1_b32 s64, 0
	v_and_or_b32 v172, v43, s69, v42
	s_cselect_b32 s65, 0xe000, 0
	v_lshl_add_u64 v[42:43], s[58:59], 0, v[172:173]
	s_add_i32 s65, s36, s65
	s_cmp_lt_u32 s28, 64
	s_cbranch_scc1 .Lscan_nodma
	s_mov_b32 m0, s65
	s_nop 0
	global_load_lds_dwordx4 v[42:43], off
	global_load_lds_dwordx4 v[42:43], off offset:-4096
	v_add_u32_e32 v42, s37, v41
	v_lshrrev_b32_e32 v43, 8, v42
	v_xor_b32_e32 v43, v43, v40
	v_lshlrev_b32_e32 v43, 4, v43
	v_and_b32_e32 v42, 0xffffff00, v42
	v_and_or_b32 v172, v43, s69, v42
	v_lshl_add_u64 v[42:43], s[58:59], 0, v[172:173]
	s_add_i32 s66, s65, 0x2000
	s_mov_b32 m0, s66
	s_nop 0
	global_load_lds_dwordx4 v[42:43], off
	global_load_lds_dwordx4 v[42:43], off offset:-4096
	v_add_u32_e32 v42, s39, v41
	v_lshrrev_b32_e32 v43, 8, v42
	v_xor_b32_e32 v43, v43, v40
	v_lshlrev_b32_e32 v43, 4, v43
	v_and_b32_e32 v42, 0xffffff00, v42
	v_and_or_b32 v172, v43, s69, v42
	v_lshl_add_u64 v[42:43], s[58:59], 0, v[172:173]
	s_add_i32 s66, s65, 0x4000
	s_mov_b32 m0, s66
	s_nop 0
	global_load_lds_dwordx4 v[42:43], off
	global_load_lds_dwordx4 v[42:43], off offset:-4096
	v_add_u32_e32 v42, s41, v41
	v_lshrrev_b32_e32 v43, 8, v42
	v_xor_b32_e32 v43, v43, v40
	v_lshlrev_b32_e32 v43, 4, v43
	v_and_b32_e32 v42, 0xffffff00, v42
	v_and_or_b32 v172, v43, s69, v42
	v_lshl_add_u64 v[42:43], s[58:59], 0, v[172:173]
	s_add_i32 s66, s65, 0x6000
	s_mov_b32 m0, s66
	s_nop 0
	global_load_lds_dwordx4 v[42:43], off
	global_load_lds_dwordx4 v[42:43], off offset:-4096
	v_add_u32_e32 v42, s45, v41
	v_lshrrev_b32_e32 v43, 8, v42
	v_xor_b32_e32 v43, v43, v40
	v_lshlrev_b32_e32 v43, 4, v43
	v_and_b32_e32 v42, 0xffffff80, v42
	v_and_or_b32 v172, v43, s93, v42
	v_lshl_add_u64 v[42:43], s[58:59], 0, v[172:173]
	s_add_i32 s66, s65, 0x8000
	s_mov_b32 m0, s66
	s_nop 0
	global_load_lds_dwordx4 v[42:43], off
	global_load_lds_dwordx4 v[42:43], off offset:-4096
	v_add_u32_e32 v42, s47, v41
	v_lshrrev_b32_e32 v43, 8, v42
	v_xor_b32_e32 v43, v43, v40
	v_lshlrev_b32_e32 v43, 4, v43
	v_and_b32_e32 v42, 0xffffff80, v42
	v_and_or_b32 v172, v43, s93, v42
	v_lshl_add_u64 v[42:43], s[58:59], 0, v[172:173]
	v_add_u32_e32 v41, s49, v41
	s_add_i32 s66, s65, 0xa000
	s_mov_b32 m0, s66
	s_nop 0
	global_load_lds_dwordx4 v[42:43], off
	global_load_lds_dwordx4 v[42:43], off offset:-4096
	v_lshrrev_b32_e32 v42, 8, v41
	v_xor_b32_e32 v42, v42, v40
	v_lshlrev_b32_e32 v42, 4, v42
	v_and_b32_e32 v41, 0xffffff80, v41
	v_and_or_b32 v172, v42, s93, v41
	v_lshl_add_u64 v[42:43], s[58:59], 0, v[172:173]
	s_add_i32 s65, s65, 0xc000
	s_mov_b32 m0, s65
	s_nop 0
	global_load_lds_dwordx4 v[42:43], off
	global_load_lds_dwordx4 v[42:43], off offset:-4096
.Lscan_nodma:
	v_or_b32_e32 v41, s28, v135
	v_lshlrev_b32_e32 v42, 3, v136
	v_lshl_add_u32 v172, v41, 6, v42
	v_lshl_add_u64 v[42:43], v[172:173], 1, s[20:21]
	global_load_dwordx4 v[126:129], v[42:43], off
	global_load_dwordx4 v[130:133], v[42:43], off offset:64
